# MLA fast loop: row-sum partial accumulators kept live across key tiles, reduced once per unit at loop exit (34 vs 38 VALU per tile)
# baseline (speedup 1.0000x reference)
.Lf_entry:
	v_mov_b32_e32 v244, 0
	v_mov_b32_e32 v245, 0
	v_mov_b32_e32 v246, 0
	v_mov_b32_e32 v247, 0
	v_mov_b32_e32 v250, 0
	v_mov_b32_e32 v251, 0
	v_mov_b32_e32 v252, 0
	v_mov_b32_e32 v253, 0
	v_mov_b32_e32 v240, 0
	v_mov_b32_e32 v241, 0
	v_mov_b32_e32 v10, 0
	v_mov_b32_e32 v211, 0
	v_lshlrev_b32_e32 v249, 1, v198

.Lf_966:
	s_or_b64 exec, exec, s[44:45]
	s_waitcnt vmcnt(0)
	ds_write_b128 v215, v[192:195] offset:35840
	v_pk_add_f32 v[244:245], v[244:245], v[88:89]
	v_pk_add_f32 v[246:247], v[246:247], v[90:91]
	v_pk_add_f32 v[244:245], v[244:245], v[92:93]
	v_pk_add_f32 v[246:247], v[246:247], v[94:95]
	v_pk_add_f32 v[244:245], v[244:245], v[112:113]
	v_pk_add_f32 v[246:247], v[246:247], v[114:115]
	v_pk_add_f32 v[244:245], v[244:245], v[116:117]
	v_pk_add_f32 v[246:247], v[246:247], v[118:119]
	v_pk_add_f32 v[244:245], v[244:245], v[120:121]
	v_pk_add_f32 v[246:247], v[246:247], v[122:123]
	v_pk_add_f32 v[244:245], v[244:245], v[124:125]
	v_pk_add_f32 v[246:247], v[246:247], v[126:127]
	v_pk_add_f32 v[244:245], v[244:245], v[140:141]
	v_pk_add_f32 v[246:247], v[246:247], v[142:143]
	v_add_f32_e32 v244, v80, v244
	v_add_f32_e32 v246, v106, v246
	v_pk_add_f32 v[250:251], v[250:251], v[12:13]
	v_pk_add_f32 v[252:253], v[252:253], v[14:15]
	v_pk_add_f32 v[250:251], v[250:251], v[82:83]
	v_pk_add_f32 v[252:253], v[252:253], v[84:85]
	v_pk_add_f32 v[250:251], v[250:251], v[96:97]
	v_pk_add_f32 v[252:253], v[252:253], v[98:99]
	v_pk_add_f32 v[250:251], v[250:251], v[100:101]
	v_pk_add_f32 v[252:253], v[252:253], v[102:103]
	v_pk_add_f32 v[250:251], v[250:251], v[104:105]
	v_pk_add_f32 v[252:253], v[252:253], v[128:129]
	v_pk_add_f32 v[250:251], v[250:251], v[130:131]
	v_pk_add_f32 v[252:253], v[252:253], v[132:133]
	v_pk_add_f32 v[250:251], v[250:251], v[134:135]
	v_pk_add_f32 v[252:253], v[252:253], v[136:137]
	v_add_f32_e32 v250, v11, v250
	v_add_f32_e32 v252, v237, v252
	v_pk_add_f32 v[240:241], v[240:241], v[86:87]
	v_pk_add_f32 v[240:241], v[240:241], v[138:139]
	v_lshl_add_u64 v[200:201], v[200:201], 0, s[10:11]
	s_cmp_eq_u32 s33, 63
	v_lshl_add_u64 v[202:203], v[202:203], 0, s[12:13]
	s_waitcnt lgkmcnt(0)
	s_barrier
	s_cbranch_scc1 .Lf_exit
	global_load_dwordx4 v[2:5], v[202:203], off
	global_load_dwordx4 v[192:195], v[200:201], off
	s_add_i32 s33, s33, 1
	s_and_saveexec_b64 s[44:45], s[0:1]
	s_cbranch_execz .Lf_962o
	s_mul_i32 s6, s33, 0x1800
	s_lshl_b64 s[54:55], s[6:7], 1
	s_add_u32 s54, s42, s54
	s_addc_u32 s55, s43, s55
	global_load_dwordx4 v[6:9], v249, s[54:55]

.Lf_966o:
	s_or_b64 exec, exec, s[44:45]
	s_waitcnt vmcnt(0)
	ds_write_b128 v215, v[192:195] offset:26624
	v_pk_add_f32 v[244:245], v[244:245], v[88:89]
	v_pk_add_f32 v[246:247], v[246:247], v[90:91]
	v_pk_add_f32 v[244:245], v[244:245], v[92:93]
	v_pk_add_f32 v[246:247], v[246:247], v[94:95]
	v_pk_add_f32 v[244:245], v[244:245], v[112:113]
	v_pk_add_f32 v[246:247], v[246:247], v[114:115]
	v_pk_add_f32 v[244:245], v[244:245], v[116:117]
	v_pk_add_f32 v[246:247], v[246:247], v[118:119]
	v_pk_add_f32 v[244:245], v[244:245], v[120:121]
	v_pk_add_f32 v[246:247], v[246:247], v[122:123]
	v_pk_add_f32 v[244:245], v[244:245], v[124:125]
	v_pk_add_f32 v[246:247], v[246:247], v[126:127]
	v_pk_add_f32 v[244:245], v[244:245], v[140:141]
	v_pk_add_f32 v[246:247], v[246:247], v[142:143]
	v_add_f32_e32 v244, v80, v244
	v_add_f32_e32 v246, v106, v246
	v_pk_add_f32 v[250:251], v[250:251], v[12:13]
	v_pk_add_f32 v[252:253], v[252:253], v[14:15]
	v_pk_add_f32 v[250:251], v[250:251], v[82:83]
	v_pk_add_f32 v[252:253], v[252:253], v[84:85]
	v_pk_add_f32 v[250:251], v[250:251], v[96:97]
	v_pk_add_f32 v[252:253], v[252:253], v[98:99]
	v_pk_add_f32 v[250:251], v[250:251], v[100:101]
	v_pk_add_f32 v[252:253], v[252:253], v[102:103]
	v_pk_add_f32 v[250:251], v[250:251], v[104:105]
	v_pk_add_f32 v[252:253], v[252:253], v[128:129]
	v_pk_add_f32 v[250:251], v[250:251], v[130:131]
	v_pk_add_f32 v[252:253], v[252:253], v[132:133]
	v_pk_add_f32 v[250:251], v[250:251], v[134:135]
	v_pk_add_f32 v[252:253], v[252:253], v[136:137]
	v_add_f32_e32 v250, v11, v250
	v_add_f32_e32 v252, v237, v252
	v_pk_add_f32 v[240:241], v[240:241], v[86:87]
	v_pk_add_f32 v[240:241], v[240:241], v[138:139]
	v_lshl_add_u64 v[200:201], v[200:201], 0, s[10:11]
	v_lshl_add_u64 v[202:203], v[202:203], 0, s[12:13]
	s_waitcnt lgkmcnt(0)
	s_barrier
	s_mov_b32 s24, s33
	s_branch .Lf_960
.Lf_exit:
	v_add_f32_e32 v248, v244, v245
	v_add_f32_e32 v248, v246, v248
	v_add_f32_e32 v248, v247, v248
	v_add_f32_e32 v248, v241, v248
	v_add_f32_e32 v206, v206, v248
	v_add_f32_e32 v248, v250, v251
	v_add_f32_e32 v248, v252, v248
	v_add_f32_e32 v248, v253, v248
	v_add_f32_e32 v248, v240, v248
	v_add_f32_e32 v0, v0, v248
